# grid barrier poll back-off s_sleep 40 -> 4
# baseline (speedup 1.0000x reference)
.LBB0_20:
	s_sleep 4
	global_load_dword v0, v145, s[4:5] sc1
	s_waitcnt vmcnt(0)
	v_cmp_gt_u32_e32 vcc, s2, v0
	s_cbranch_vccnz .LBB0_20
